# attention DMA issue folded into the deferred PV group, K-pair waits merged; redundant second grid barrier per seam reduced to arrive-only
# speedup vs baseline: 1.0128x; 1.0128x over previous
.LBB0_137:
	s_andn2_b64 vcc, exec, s[0:1]
	s_lshl_b32 s74, s78, 1
	s_barrier
	s_barrier
	s_cbranch_vccnz .LBB0_145
	v_mbcnt_lo_u32_b32 v0, -1, 0
	v_mbcnt_hi_u32_b32 v0, -1, v0
	s_nop 0
	v_cmp_eq_u32_e32 vcc, 0, v0
	s_and_saveexec_b64 s[0:1], vcc
	s_cbranch_execz .LBB0_144
	s_mov_b64 s[4:5], exec
	v_mbcnt_lo_u32_b32 v0, s4, 0
	v_mbcnt_hi_u32_b32 v0, s5, v0
	v_cmp_eq_u32_e32 vcc, 0, v0
	s_and_saveexec_b64 s[6:7], vcc
	s_cbranch_execz .LBB0_141
	s_bcnt1_i32_b64 s4, s[4:5]
	v_mov_b32_e32 v0, 0
	v_mov_b32_e32 v1, s4
	global_atomic_add v0, v1, s[22:23]
.LBB0_141:
	s_or_b64 exec, exec, s[6:7]
	v_mov_b32_e32 v0, 0
.LBB0_144:
	s_or_b64 exec, exec, s[0:1]

.LBB0_564:
	s_andn2_b64 vcc, exec, s[2:3]
	s_add_i32 s74, s12, s78
	s_barrier
	s_barrier
	s_cbranch_vccnz .LBB0_572
	v_mbcnt_lo_u32_b32 v0, -1, 0
	v_mbcnt_hi_u32_b32 v0, -1, v0
	s_nop 0
	v_cmp_eq_u32_e32 vcc, 0, v0
	s_and_saveexec_b64 s[2:3], vcc
	s_cbranch_execz .LBB0_571
	s_mov_b64 s[4:5], exec
	v_mbcnt_lo_u32_b32 v0, s4, 0
	v_mbcnt_hi_u32_b32 v0, s5, v0
	v_cmp_eq_u32_e32 vcc, 0, v0
	s_and_saveexec_b64 s[6:7], vcc
	s_cbranch_execz .LBB0_568
	s_bcnt1_i32_b64 s4, s[4:5]
	v_mov_b32_e32 v0, 0
	v_mov_b32_e32 v1, s4
	global_atomic_add v0, v1, s[22:23]
.LBB0_568:
	s_or_b64 exec, exec, s[6:7]
	v_mov_b32_e32 v0, 0
.LBB0_571:
	s_or_b64 exec, exec, s[2:3]

.LBB0_797:
	s_andn2_b64 vcc, exec, s[2:3]
	s_add_i32 s74, s10, s78
	s_barrier
	s_barrier
	s_cbranch_vccnz .LBB0_805
	v_mbcnt_lo_u32_b32 v0, -1, 0
	v_mbcnt_hi_u32_b32 v0, -1, v0
	s_nop 0
	v_cmp_eq_u32_e32 vcc, 0, v0
	s_and_saveexec_b64 s[2:3], vcc
	s_cbranch_execz .LBB0_804
	s_mov_b64 s[4:5], exec
	v_mbcnt_lo_u32_b32 v0, s4, 0
	v_mbcnt_hi_u32_b32 v0, s5, v0
	v_cmp_eq_u32_e32 vcc, 0, v0
	s_and_saveexec_b64 s[6:7], vcc
	s_cbranch_execz .LBB0_801
	s_bcnt1_i32_b64 s4, s[4:5]
	v_mov_b32_e32 v0, 0
	v_mov_b32_e32 v1, s4
	global_atomic_add v0, v1, s[22:23]
.LBB0_801:
	s_or_b64 exec, exec, s[6:7]
	v_mov_b32_e32 v0, 0
.LBB0_804:
	s_or_b64 exec, exec, s[2:3]

; __device__ __forceinline__ int lane_id_v() { int l; asm volatile("v_mbcnt_lo_u32_b32 %0, -1, 0\n\tv_mbcnt_hi_u32_b32 %0, -1, %0" : "=v"(l)); return l; }
; __device__ __forceinline__ int v_rd_base(int lane) { return ((lane & 3) << 3) | (((lane >> 2) & 3) << 6) | (((lane >> 4) & 1) << 5) | (((lane >> 5) & 1) << 8); }
; #define WAITV() asm volatile("s_waitcnt vmcnt(0)" ::: "memory")
; template <int DN, int DV, bool MASK> ...
;     ...
;   const int wid = wave_, lane = lane_id_v(), r32 = lane & 31, hi = lane >> 5;
;   char* Vl = lds; char* Knl = lds + VB; char* Krl = lds + VB + KNB;
;   float* wsf = (float*)(lds + 3 * BUF) + wid * 64; float* li_l = wsf; float* al_l = wsf + 32;
;   float m_reg = -1e30f, l_reg = 0; f32x16 o[NCB] = {}; bf16x8 qr[NQR];
;   const bf16_t* Qw = Qb + (MASK ? (long)r32 * ldq + wid * 64 : (long)(wid * 32 + r32) * ldq) + hi * 8;
; #pragma unroll
;   for (int d0 = 0; d0 < NQR; ++d0) qr[d0] = *reinterpret_cast<const bf16x8*>(Qw + d0 * 16);
;   char* qrl = lds + 3 * BUF + 2048 + wid * 4096 + lane * 16;
;   if constexpr (DN > 0) {
; #pragma unroll
;     for (int d0 = 0; d0 < 4; ++d0) *reinterpret_cast<bf16x8*>(qrl + d0 * 1024) = *reinterpret_cast<const bf16x8*>(Qw + DN + d0 * 16);
;   }
;   int offV[NVC], offK[NKC > 0 ? NKC : 1], offR;
; #pragma unroll
;   for (int i = 0; i < NVC; ++i) { const int ch = wid * NVC + i, sub = ch * 2 + (lane >> 5), kk = (sub / NCB) * 8 + ((lane & 31) >> 2), col = (sub % NCB) * 32 + (lane & 3) * 8;
;     const int k = (kk & ~0xC) | ((kk & 4) << 1) | ((kk & 8) >> 1); offV[i] = k * ldv + col; }
; #pragma unroll
;   for (int i = 0; i < NKC; ++i) { const int ch = wid * NKC + i, row = ch * 4 + (lane >> 4), cb = ((lane & 15) * 16) ^ ((row & 15) << 4); offK[i] = row * ldkn + (cb >> 1); }
;   { const int row = wid * 8 + (lane >> 3), cb = ((lane & 7) * 16) ^ (((row >> 1) & 7) << 4); offR = row * ldkr + (cb >> 1); }
;   const int vb0 = (int)(uintptr_t)Vl + v_rd_base(lane);
;   const int qd = qpos0 + (MASK ? 0 : wid * 32) + r32 - 4 * hi;
;     ...
;   const int q0w = qpos0 + (MASK ? 0 : wid * 32);
;     ...
;   f32x16 pA0, pA1, pB0, pB1; float alA, alB; bf16x8 pa0, pa1, pa2, pa3;
;   int bp = 0, bc = BUF, bn = 2 * BUF;
;   DMA(0, 0); DMA(1, BUF); WAITV(); __syncthreads();
.LBB0_818:
	s_and_b32 s97, s2, 15
	s_ashr_i32 s69, s68, 31
	s_mul_i32 s1, s68, 0x1800
	s_mul_hi_i32 s0, s68, 0x1800
	s_add_u32 s1, s34, s1
	s_addc_u32 s2, s35, s0
	s_mul_i32 s0, s97, 0x180
	s_add_u32 s0, s1, s0
	s_addc_u32 s1, s2, 0
	v_mbcnt_lo_u32_b32 v249, -1, 0
	v_mbcnt_hi_u32_b32 v249, -1, v249
	s_waitcnt lgkmcnt(0)
	v_and_b32_e32 v173, 31, v249
	v_lshrrev_b32_e32 v174, 5, v249
	v_or_b32_e32 v175, s46, v173
	v_mov_b64_e32 v[64:65], s[0:1]
	s_movk_i32 s12, 0x1800
	v_mad_u64_u32 v[64:65], s[14:15], v175, s12, v[64:65]
	v_lshlrev_b32_e32 v66, 4, v174
	v_mov_b32_e32 v67, 0
	v_lshl_add_u64 v[64:65], v[64:65], 0, v[66:67]
	global_load_dwordx4 v[96:99], v[64:65], off offset:0
	global_load_dwordx4 v[100:103], v[64:65], off offset:32
	global_load_dwordx4 v[104:107], v[64:65], off offset:64
	global_load_dwordx4 v[108:111], v[64:65], off offset:96
	global_load_dwordx4 v[112:115], v[64:65], off offset:128
	global_load_dwordx4 v[116:119], v[64:65], off offset:160
	global_load_dwordx4 v[120:123], v[64:65], off offset:192
	global_load_dwordx4 v[124:127], v[64:65], off offset:224
	global_load_dwordx4 v[176:179], v[64:65], off offset:256
	global_load_dwordx4 v[180:183], v[64:65], off offset:288
	global_load_dwordx4 v[184:187], v[64:65], off offset:320
	global_load_dwordx4 v[188:191], v[64:65], off offset:352
	v_and_b32_e32 v66, 15, v173
	v_xor_b32_e32 v66, v66, v174
	v_lshlrev_b32_e32 v66, 4, v66
	v_lshl_or_b32 v152, v173, 8, v66
	v_xor_b32_e32 v153, 32, v152
	v_xor_b32_e32 v154, 64, v152
	v_xor_b32_e32 v155, 96, v152
	v_xor_b32_e32 v156, 128, v152
	v_xor_b32_e32 v157, 160, v152
	v_xor_b32_e32 v158, 192, v152
	v_xor_b32_e32 v159, 224, v152
	v_bfe_u32 v66, v173, 1, 3
	v_xor_b32_e32 v66, v66, v174
	v_lshlrev_b32_e32 v66, 4, v66
	v_lshl_or_b32 v160, v173, 7, v66
	v_xor_b32_e32 v161, 32, v160
	v_xor_b32_e32 v162, 64, v160
	v_xor_b32_e32 v163, 96, v160
	v_lshlrev_b32_e32 v66, 3, v249
	v_and_b32_e32 v67, 24, v66
	v_and_b32_e32 v68, 0x100, v66
	v_or_b32_e32 v67, v67, v68
	v_lshlrev_b32_e32 v68, 4, v249
	v_and_b32_e32 v68, 0xc0, v68
	v_or_b32_e32 v67, v67, v68
	v_lshlrev_b32_e32 v68, 1, v249
	v_and_b32_e32 v68, 32, v68
	v_or_b32_e32 v67, v67, v68
	v_add_u32_e32 v164, 0xc000, v67
	v_lshl_add_u32 v248, v249, 4, s75
	v_lshrrev_b32_e32 v66, 2, v173
	v_add_u32_e32 v66, s77, v66
	v_and_b32_e32 v67, 4, v66
	v_and_b32_e32 v68, 8, v66
	v_and_b32_e32 v66, 0xfffffff3, v66
	v_lshl_or_b32 v66, v67, 1, v66
	v_lshrrev_b32_e32 v68, 1, v68
	v_or_b32_e32 v66, v66, v68
	v_and_b32_e32 v67, 3, v249
	v_lshlrev_b32_e32 v67, 4, v67
	v_lshl_or_b32 v67, v174, 6, v67
	v_lshl_add_u32 v66, v66, 13, v67
	v_add_u32_e32 v165, 0x100, v66
	v_add_u32_e32 v169, 0x180, v66
	v_lshrrev_b32_e32 v66, 4, v249
	v_add_u32_e32 v66, s77, v66
	v_and_b32_e32 v67, 15, v249
	v_xor_b32_e32 v68, v67, v66
	v_and_b32_e32 v68, 15, v68
	v_lshlrev_b32_e32 v68, 4, v68
	v_lshl_add_u32 v166, v66, 13, v68
	v_add_u32_e32 v66, 4, v66
	v_xor_b32_e32 v68, v67, v66
	v_and_b32_e32 v68, 15, v68
	v_lshlrev_b32_e32 v68, 4, v68
	v_lshl_add_u32 v167, v66, 13, v68
	v_lshrrev_b32_e32 v66, 3, v249
	v_add_u32_e32 v66, s77, v66
	v_bfe_u32 v67, v66, 1, 3
	v_and_b32_e32 v68, 7, v249
	v_xor_b32_e32 v67, v67, v68
	v_lshlrev_b32_e32 v67, 4, v67
	v_lshl_add_u32 v168, v66, 7, v67
	s_lshl_b32 s0, s97, 9
	s_add_u32 s79, s38, s0
	s_addc_u32 s26, s39, 0
	s_ashr_i32 s71, s70, 31
	s_lshl_b64 s[0:1], s[70:71], 13
	s_add_u32 s4, s79, s0
	s_addc_u32 s5, s26, s1
	s_add_u32 s6, s4, 0x80000
	s_addc_u32 s7, s5, 0
	s_lshl_b64 s[0:1], s[70:71], 7
	s_add_u32 s8, s18, s0
	s_addc_u32 s9, s19, s1
	s_add_i32 m0, s82, 0
	s_nop 0
	global_load_lds_dwordx4 v166, s[4:5]
	s_add_i32 m0, s82, 1024
	s_nop 0
	global_load_lds_dwordx4 v167, s[4:5]
	s_add_i32 m0, s83, 16384
	s_nop 0
	global_load_lds_dwordx4 v168, s[8:9]
	s_add_u32 s8, s8, 0x2000
	s_addc_u32 s9, s9, 0
	s_mov_b32 s10, 0
	v_mov_b32_e32 v0, 0
	v_mov_b32_e32 v1, 0
	v_mov_b32_e32 v2, 0
	v_mov_b32_e32 v3, 0
	v_mov_b32_e32 v4, 0
	v_mov_b32_e32 v5, 0
	v_mov_b32_e32 v6, 0
	v_mov_b32_e32 v7, 0
	v_mov_b32_e32 v8, 0
	v_mov_b32_e32 v9, 0
	v_mov_b32_e32 v10, 0
	v_mov_b32_e32 v11, 0
	v_mov_b32_e32 v12, 0
	v_mov_b32_e32 v13, 0
	v_mov_b32_e32 v14, 0
	v_mov_b32_e32 v15, 0
	v_mov_b32_e32 v48, 0
	v_mov_b32_e32 v49, 0
	v_mov_b32_e32 v50, 0
	v_mov_b32_e32 v51, 0
	v_mov_b32_e32 v52, 0
	v_mov_b32_e32 v53, 0
	v_mov_b32_e32 v54, 0
	v_mov_b32_e32 v55, 0
	v_mov_b32_e32 v56, 0
	v_mov_b32_e32 v57, 0
	v_mov_b32_e32 v58, 0
	v_mov_b32_e32 v59, 0
	v_mov_b32_e32 v60, 0
	v_mov_b32_e32 v61, 0
	v_mov_b32_e32 v62, 0
	v_mov_b32_e32 v63, 0
	v_mov_b32_e32 v32, 0
	v_mov_b32_e32 v33, 0
	v_mov_b32_e32 v34, 0
	v_mov_b32_e32 v35, 0
	v_mov_b32_e32 v36, 0
	v_mov_b32_e32 v37, 0
	v_mov_b32_e32 v38, 0
	v_mov_b32_e32 v39, 0
	v_mov_b32_e32 v40, 0
	v_mov_b32_e32 v41, 0
	v_mov_b32_e32 v42, 0
	v_mov_b32_e32 v43, 0
	v_mov_b32_e32 v44, 0
	v_mov_b32_e32 v45, 0
	v_mov_b32_e32 v46, 0
	v_mov_b32_e32 v47, 0
	v_mov_b32_e32 v16, 0
	v_mov_b32_e32 v17, 0
	v_mov_b32_e32 v18, 0
	v_mov_b32_e32 v19, 0
	v_mov_b32_e32 v20, 0
	v_mov_b32_e32 v21, 0
	v_mov_b32_e32 v22, 0
	v_mov_b32_e32 v23, 0
	v_mov_b32_e32 v24, 0
	v_mov_b32_e32 v25, 0
	v_mov_b32_e32 v26, 0
	v_mov_b32_e32 v27, 0
	v_mov_b32_e32 v28, 0
	v_mov_b32_e32 v29, 0
	v_mov_b32_e32 v30, 0
	v_mov_b32_e32 v31, 0
	v_mov_b32_e32 v170, 0
	s_waitcnt vmcnt(0)
	ds_write_b128 v248, v[176:179] offset:0
	ds_write_b128 v248, v[180:183] offset:1024
	ds_write_b128 v248, v[184:187] offset:2048
	ds_write_b128 v248, v[188:191] offset:3072
	s_waitcnt lgkmcnt(0)
	s_barrier
; __device__ __forceinline__ void partialSM(f32x16& p0, f32x16& p1, float& m_reg, float& alpha, const float C, const float THRS) {
;   float pmax = p0[0];
; #pragma unroll
;   for (int r = 1; r < 16; ++r) pmax = fmaxf(pmax, p0[r]);
; #pragma unroll
;   for (int r = 0; r < 16; ++r) pmax = fmaxf(pmax, p1[r]);
;   { auto rr = __builtin_amdgcn_permlane32_swap(__float_as_uint(pmax), __float_as_uint(pmax), false, false);
;     pmax = fmaxf(__uint_as_float(rr[0]), __uint_as_float(rr[1])); }
;   float mn;
;   if (__builtin_expect(__all(pmax - m_reg <= THRS), 1)) { mn = m_reg; alpha = 1.f; }
;   else { mn = fmaxf(m_reg, pmax); alpha = __builtin_amdgcn_exp2f((m_reg - mn) * C); m_reg = mn; }
;   const float mnC = -mn * C;
; #pragma unroll
;   for (int r = 0; r < 16; ++r) p0[r] = fmaf(p0[r], C, mnC);
; #pragma unroll
;   for (int r = 0; r < 16; ++r) p1[r] = fmaf(p1[r], C, mnC);
; #pragma unroll
;   for (int r = 0; r < 16; ++r) p0[r] = __builtin_amdgcn_exp2f(p0[r]);
; }
; template <int DN>
; __device__ __forceinline__ void qkt(f32x16& p0, f32x16& p1, const char* Kn, const char* Kr, const bf16x8* qr, const char* qrl, int r32, int hi) {
;   p0 = f32x16{}; p1 = f32x16{};
;   if constexpr (DN > 0) {
; #pragma unroll
;     for (int d0 = 0; d0 < DN / 16; ++d0) { const int cb = (d0 * 16 + hi * 8) * 2;
;       bf16x8 b0 = *reinterpret_cast<const bf16x8*>(Kn + KSWZ(r32, cb));
;       bf16x8 b1 = *reinterpret_cast<const bf16x8*>(Kn + KSWZ(32 + r32, cb));
;       p0 = __builtin_amdgcn_mfma_f32_32x32x16_bf16(b0, qr[d0], p0, 0, 0, 0);
;       p1 = __builtin_amdgcn_mfma_f32_32x32x16_bf16(b1, qr[d0], p1, 0, 0, 0); }
;   }
; #pragma unroll
;   for (int d0 = 0; d0 < 4; ++d0) { const int cb = (d0 * 16 + hi * 8) * 2;
;     bf16x8 b0 = *reinterpret_cast<const bf16x8*>(Kr + KSWZ64(r32, cb));
;     bf16x8 b1 = *reinterpret_cast<const bf16x8*>(Kr + KSWZ64(32 + r32, cb));
;     bf16x8 q; if constexpr (DN > 0) q = *reinterpret_cast<const bf16x8*>(qrl + d0 * 1024); else q = qr[d0];
;     p0 = __builtin_amdgcn_mfma_f32_32x32x16_bf16(b0, q, p0, 0, 0, 0);
;     p1 = __builtin_amdgcn_mfma_f32_32x32x16_bf16(b1, q, p1, 0, 0, 0); }
; }
	ds_read_b128 v[224:227], v152 offset:0
	ds_read_b128 v[228:231], v152 offset:8192
	ds_read_b128 v[232:235], v153 offset:0
	ds_read_b128 v[236:239], v153 offset:8192
	ds_read_b128 v[240:243], v154 offset:0
	ds_read_b128 v[244:247], v154 offset:8192
	s_add_i32 m0, s82, 49152
	s_nop 0
	global_load_lds_dwordx4 v165, s[4:5]
	s_add_i32 m0, s82, 50176
	s_nop 0
	global_load_lds_dwordx4 v169, s[4:5]
	s_add_i32 m0, s82, 24576
	s_nop 0
	global_load_lds_dwordx4 v166, s[6:7]
	s_add_i32 m0, s82, 25600
	s_nop 0
	global_load_lds_dwordx4 v167, s[6:7]
	s_add_i32 m0, s83, 40960
	s_nop 0
	global_load_lds_dwordx4 v168, s[8:9]
	s_mov_b64 s[4:5], s[6:7]
	s_add_u32 s6, s6, 0x80000
	s_addc_u32 s7, s7, 0
	s_add_u32 s8, s8, 0x2000
	s_addc_u32 s9, s9, 0
	s_waitcnt lgkmcnt(4)
	v_mfma_f32_32x32x16_bf16 v[64:79], v[224:227], v[96:99], 0
	v_mfma_f32_32x32x16_bf16 v[80:95], v[228:231], v[96:99], 0
	ds_read_b128 v[224:227], v155 offset:0
	ds_read_b128 v[228:231], v155 offset:8192
	s_waitcnt lgkmcnt(4)
	v_mfma_f32_32x32x16_bf16 v[64:79], v[232:235], v[100:103], v[64:79]
	v_mfma_f32_32x32x16_bf16 v[80:95], v[236:239], v[100:103], v[80:95]
	ds_read_b128 v[232:235], v156 offset:0
	ds_read_b128 v[236:239], v156 offset:8192
	s_waitcnt lgkmcnt(4)
	v_mfma_f32_32x32x16_bf16 v[64:79], v[240:243], v[104:107], v[64:79]
	v_mfma_f32_32x32x16_bf16 v[80:95], v[244:247], v[104:107], v[80:95]
	ds_read_b128 v[240:243], v157 offset:0
	ds_read_b128 v[244:247], v157 offset:8192
	s_waitcnt lgkmcnt(4)
	v_mfma_f32_32x32x16_bf16 v[64:79], v[224:227], v[108:111], v[64:79]
	v_mfma_f32_32x32x16_bf16 v[80:95], v[228:231], v[108:111], v[80:95]
	ds_read_b128 v[224:227], v158 offset:0
	ds_read_b128 v[228:231], v158 offset:8192
	s_waitcnt lgkmcnt(4)
	v_mfma_f32_32x32x16_bf16 v[64:79], v[232:235], v[112:115], v[64:79]
	v_mfma_f32_32x32x16_bf16 v[80:95], v[236:239], v[112:115], v[80:95]
	ds_read_b128 v[232:235], v159 offset:0
	ds_read_b128 v[236:239], v159 offset:8192
	s_waitcnt lgkmcnt(4)
	v_mfma_f32_32x32x16_bf16 v[64:79], v[240:243], v[116:119], v[64:79]
	v_mfma_f32_32x32x16_bf16 v[80:95], v[244:247], v[116:119], v[80:95]
	ds_read_b128 v[252:255], v248 offset:0
	ds_read_b128 v[240:243], v160 offset:16384
	ds_read_b128 v[244:247], v160 offset:20480
	s_waitcnt lgkmcnt(5)
	v_mfma_f32_32x32x16_bf16 v[64:79], v[224:227], v[120:123], v[64:79]
	v_mfma_f32_32x32x16_bf16 v[80:95], v[228:231], v[120:123], v[80:95]
	ds_read_b128 v[144:147], v248 offset:1024
	ds_read_b128 v[224:227], v161 offset:16384
	ds_read_b128 v[228:231], v161 offset:20480
	s_waitcnt lgkmcnt(6)
	v_mfma_f32_32x32x16_bf16 v[64:79], v[232:235], v[124:127], v[64:79]
	v_mfma_f32_32x32x16_bf16 v[80:95], v[236:239], v[124:127], v[80:95]
	ds_read_b128 v[148:151], v248 offset:2048
	ds_read_b128 v[232:235], v162 offset:16384
	ds_read_b128 v[236:239], v162 offset:20480
	s_waitcnt lgkmcnt(6)
	v_mfma_f32_32x32x16_bf16 v[64:79], v[240:243], v[252:255], v[64:79]
	v_mfma_f32_32x32x16_bf16 v[80:95], v[244:247], v[252:255], v[80:95]
	ds_read_b128 v[252:255], v248 offset:3072
	ds_read_b128 v[240:243], v163 offset:16384
	ds_read_b128 v[244:247], v163 offset:20480
	s_waitcnt lgkmcnt(6)
	v_mfma_f32_32x32x16_bf16 v[64:79], v[224:227], v[144:147], v[64:79]
	v_mfma_f32_32x32x16_bf16 v[80:95], v[228:231], v[144:147], v[80:95]
	s_waitcnt lgkmcnt(3)
	v_mfma_f32_32x32x16_bf16 v[64:79], v[232:235], v[148:151], v[64:79]
	v_mfma_f32_32x32x16_bf16 v[80:95], v[236:239], v[148:151], v[80:95]
	s_waitcnt lgkmcnt(0)
	v_mfma_f32_32x32x16_bf16 v[64:79], v[240:243], v[252:255], v[64:79]
	v_mfma_f32_32x32x16_bf16 v[80:95], v[244:247], v[252:255], v[80:95]
	s_nop 11
	v_max3_f32 v224, v64, v65, v66
	v_max3_f32 v225, v80, v81, v82
	v_max3_f32 v224, v224, v67, v68
	v_max3_f32 v225, v225, v83, v84
	v_max3_f32 v224, v224, v69, v70
	v_max3_f32 v225, v225, v85, v86
	v_max3_f32 v224, v224, v71, v72
	v_max3_f32 v225, v225, v87, v88
	v_max3_f32 v224, v224, v73, v74
	v_max3_f32 v225, v225, v89, v90
	v_max3_f32 v224, v224, v75, v76
	v_max3_f32 v225, v225, v91, v92
	v_max3_f32 v224, v224, v77, v78
	v_max3_f32 v225, v225, v93, v94
	v_max_f32_e32 v224, v79, v224
	v_max_f32_e32 v225, v95, v225
	v_max_f32_e32 v226, v224, v225
	v_mov_b32_e32 v227, v226
	s_nop 1
	v_permlane32_swap_b32_e32 v226, v227
	v_max_f32_e32 v226, v226, v227
	v_sub_f32_e32 v208, 0, v226
	v_sub_f32_e32 v209, 0, v226
	v_sub_f32_e32 v210, 0, v226
	v_sub_f32_e32 v211, 0, v226
	v_sub_f32_e32 v212, 0, v226
	v_sub_f32_e32 v213, 0, v226
	v_sub_f32_e32 v214, 0, v226
	v_sub_f32_e32 v215, 0, v226
	v_sub_f32_e32 v216, 0, v226
	v_sub_f32_e32 v217, 0, v226
	v_sub_f32_e32 v218, 0, v226
	v_sub_f32_e32 v219, 0, v226
	v_sub_f32_e32 v220, 0, v226
	v_sub_f32_e32 v221, 0, v226
	v_sub_f32_e32 v222, 0, v226
	v_sub_f32_e32 v223, 0, v226
	v_sub_f32_e32 v64, v64, v226
	v_sub_f32_e32 v65, v65, v226
	v_sub_f32_e32 v66, v66, v226
	v_sub_f32_e32 v67, v67, v226
	v_sub_f32_e32 v68, v68, v226
	v_sub_f32_e32 v69, v69, v226
	v_sub_f32_e32 v70, v70, v226
	v_sub_f32_e32 v71, v71, v226
	v_sub_f32_e32 v72, v72, v226
	v_sub_f32_e32 v73, v73, v226
	v_sub_f32_e32 v74, v74, v226
	v_sub_f32_e32 v75, v75, v226
	v_sub_f32_e32 v76, v76, v226
	v_sub_f32_e32 v77, v77, v226
	v_sub_f32_e32 v78, v78, v226
	v_sub_f32_e32 v79, v79, v226
	v_sub_f32_e32 v80, v80, v226
	v_sub_f32_e32 v81, v81, v226
	v_sub_f32_e32 v82, v82, v226
	v_sub_f32_e32 v83, v83, v226
	v_sub_f32_e32 v84, v84, v226
	v_sub_f32_e32 v85, v85, v226
	v_sub_f32_e32 v86, v86, v226
	v_sub_f32_e32 v87, v87, v226
	v_sub_f32_e32 v88, v88, v226
	v_sub_f32_e32 v89, v89, v226
	v_sub_f32_e32 v90, v90, v226
	v_sub_f32_e32 v91, v91, v226
	v_sub_f32_e32 v92, v92, v226
	v_sub_f32_e32 v93, v93, v226
	v_sub_f32_e32 v94, v94, v226
	v_sub_f32_e32 v95, v95, v226
	v_exp_f32_e32 v64, v64
	v_exp_f32_e32 v65, v65
	v_exp_f32_e32 v66, v66
	v_exp_f32_e32 v67, v67
	v_exp_f32_e32 v68, v68
	v_exp_f32_e32 v69, v69
	v_exp_f32_e32 v70, v70
	v_exp_f32_e32 v71, v71
	v_exp_f32_e32 v72, v72
	v_exp_f32_e32 v73, v73
	v_exp_f32_e32 v74, v74
	v_exp_f32_e32 v75, v75
	v_exp_f32_e32 v76, v76
	v_exp_f32_e32 v77, v77
	v_exp_f32_e32 v78, v78
	v_exp_f32_e32 v79, v79
	s_waitcnt vmcnt(0) lgkmcnt(0)
	s_barrier
; __device__ __forceinline__ void finishSM(f32x16& p0, f32x16& p1, float alpha, float& l_reg, bf16x8& pa0, bf16x8& pa1, bf16x8& pa2, bf16x8& pa3) {
; #pragma unroll
;   for (int r = 0; r < 16; ++r) p1[r] = __builtin_amdgcn_exp2f(p1[r]);
;   float ps = 0;
; #pragma unroll
;   for (int r = 0; r < 16; ++r) ps += p0[r];
; #pragma unroll
;   for (int r = 0; r < 16; ++r) ps += p1[r];
;   { auto rr = __builtin_amdgcn_permlane32_swap(__float_as_uint(ps), __float_as_uint(ps), false, false);
;     ps = __uint_as_float(rr[0]) + __uint_as_float(rr[1]); }
;   l_reg = l_reg * alpha + ps;
;     ...
;   PK4(p0, 0, pa0); PK4(p0, 8, pa1); PK4(p1, 0, pa2); PK4(p1, 8, pa3);
;     ...
; }
; template <int DN>
; __device__ __forceinline__ void qkt(f32x16& p0, f32x16& p1, const char* Kn, const char* Kr, const bf16x8* qr, const char* qrl, int r32, int hi) {
;   p0 = f32x16{}; p1 = f32x16{};
;   if constexpr (DN > 0) {
; #pragma unroll
;     for (int d0 = 0; d0 < DN / 16; ++d0) { const int cb = (d0 * 16 + hi * 8) * 2;
;       bf16x8 b0 = *reinterpret_cast<const bf16x8*>(Kn + KSWZ(r32, cb));
;       bf16x8 b1 = *reinterpret_cast<const bf16x8*>(Kn + KSWZ(32 + r32, cb));
;       p0 = __builtin_amdgcn_mfma_f32_32x32x16_bf16(b0, qr[d0], p0, 0, 0, 0);
;       p1 = __builtin_amdgcn_mfma_f32_32x32x16_bf16(b1, qr[d0], p1, 0, 0, 0); }
;   }
; #pragma unroll
;   for (int d0 = 0; d0 < 4; ++d0) { const int cb = (d0 * 16 + hi * 8) * 2;
;     bf16x8 b0 = *reinterpret_cast<const bf16x8*>(Kr + KSWZ64(r32, cb));
;     bf16x8 b1 = *reinterpret_cast<const bf16x8*>(Kr + KSWZ64(32 + r32, cb));
;     bf16x8 q; if constexpr (DN > 0) q = *reinterpret_cast<const bf16x8*>(qrl + d0 * 1024); else q = qr[d0];
;     p0 = __builtin_amdgcn_mfma_f32_32x32x16_bf16(b0, q, p0, 0, 0, 0);
;     p1 = __builtin_amdgcn_mfma_f32_32x32x16_bf16(b1, q, p1, 0, 0, 0); }
; }
	ds_read_b128 v[224:227], v152 offset:24576
	ds_read_b128 v[228:231], v152 offset:32768
	ds_read_b128 v[232:235], v153 offset:24576
	ds_read_b128 v[236:239], v153 offset:32768
	ds_read_b128 v[240:243], v154 offset:24576
	ds_read_b128 v[244:247], v154 offset:32768
	s_add_i32 m0, s82, 65536
	s_nop 0
	global_load_lds_dwordx4 v165, s[4:5]
	s_add_i32 m0, s82, 66560
	s_nop 0
	global_load_lds_dwordx4 v169, s[4:5]
	s_add_i32 m0, s82, 0
	s_nop 0
	global_load_lds_dwordx4 v166, s[6:7]
	s_add_i32 m0, s82, 1024
	s_nop 0
	global_load_lds_dwordx4 v167, s[6:7]
	s_add_i32 m0, s83, 16384
	s_nop 0
	global_load_lds_dwordx4 v168, s[8:9]
	s_mov_b64 s[4:5], s[6:7]
	s_add_u32 s6, s6, 0x80000
	s_addc_u32 s7, s7, 0
	s_add_u32 s8, s8, 0x2000
	s_addc_u32 s9, s9, 0
	v_exp_f32_e32 v80, v80
	v_exp_f32_e32 v81, v81
	v_exp_f32_e32 v82, v82
	v_exp_f32_e32 v83, v83
	v_exp_f32_e32 v84, v84
	v_exp_f32_e32 v85, v85
	v_exp_f32_e32 v86, v86
	v_exp_f32_e32 v87, v87
	v_exp_f32_e32 v88, v88
	v_exp_f32_e32 v89, v89
	v_exp_f32_e32 v90, v90
	v_exp_f32_e32 v91, v91
	v_exp_f32_e32 v92, v92
	v_exp_f32_e32 v93, v93
	v_exp_f32_e32 v94, v94
	v_exp_f32_e32 v95, v95
	s_waitcnt lgkmcnt(4)
	v_mfma_f32_32x32x16_bf16 v[176:191], v[224:227], v[96:99], v[208:223]
	v_add_f32_e32 v170, v64, v170
	v_cvt_pk_bf16_f32 v128, v64, v65
	v_mfma_f32_32x32x16_bf16 v[192:207], v[228:231], v[96:99], v[208:223]
	ds_read_b128 v[224:227], v155 offset:24576
	ds_read_b128 v[228:231], v155 offset:32768
	v_add_f32_e32 v170, v65, v170
	v_cvt_pk_bf16_f32 v129, v66, v67
	v_add_f32_e32 v170, v66, v170
	s_waitcnt lgkmcnt(4)
	v_mfma_f32_32x32x16_bf16 v[176:191], v[232:235], v[100:103], v[176:191]
	v_cvt_pk_bf16_f32 v130, v68, v69
	v_add_f32_e32 v170, v67, v170
	v_mfma_f32_32x32x16_bf16 v[192:207], v[236:239], v[100:103], v[192:207]
	ds_read_b128 v[232:235], v156 offset:24576
	ds_read_b128 v[236:239], v156 offset:32768
	v_cvt_pk_bf16_f32 v131, v70, v71
	v_add_f32_e32 v170, v68, v170
	v_add_f32_e32 v170, v69, v170
	s_waitcnt lgkmcnt(4)
	v_mfma_f32_32x32x16_bf16 v[176:191], v[240:243], v[104:107], v[176:191]
	v_add_f32_e32 v170, v70, v170
	v_add_f32_e32 v170, v71, v170
	v_mfma_f32_32x32x16_bf16 v[192:207], v[244:247], v[104:107], v[192:207]
	ds_read_b128 v[240:243], v157 offset:24576
	ds_read_b128 v[244:247], v157 offset:32768
	v_add_f32_e32 v170, v72, v170
	v_cvt_pk_bf16_f32 v132, v72, v73
	v_add_f32_e32 v170, v73, v170
	s_waitcnt lgkmcnt(4)
	v_mfma_f32_32x32x16_bf16 v[176:191], v[224:227], v[108:111], v[176:191]
	v_cvt_pk_bf16_f32 v133, v74, v75
	v_add_f32_e32 v170, v74, v170
	v_mfma_f32_32x32x16_bf16 v[192:207], v[228:231], v[108:111], v[192:207]
	ds_read_b128 v[224:227], v158 offset:24576
	ds_read_b128 v[228:231], v158 offset:32768
	v_cvt_pk_bf16_f32 v134, v76, v77
	v_add_f32_e32 v170, v75, v170
	v_cvt_pk_bf16_f32 v135, v78, v79
	s_waitcnt lgkmcnt(4)
	v_mfma_f32_32x32x16_bf16 v[176:191], v[232:235], v[112:115], v[176:191]
	v_add_f32_e32 v170, v76, v170
	v_add_f32_e32 v170, v77, v170
	v_mfma_f32_32x32x16_bf16 v[192:207], v[236:239], v[112:115], v[192:207]
	ds_read_b128 v[232:235], v159 offset:24576
	ds_read_b128 v[236:239], v159 offset:32768
	v_add_f32_e32 v170, v78, v170
	v_add_f32_e32 v170, v79, v170
	ds_read_b64_tr_b16 v[64:65], v164 offset:0
	ds_read_b64_tr_b16 v[66:67], v164 offset:2048
	ds_read_b64_tr_b16 v[68:69], v164 offset:4096
	ds_read_b64_tr_b16 v[70:71], v164 offset:6144
	s_waitcnt lgkmcnt(8)
	v_mfma_f32_32x32x16_bf16 v[176:191], v[240:243], v[116:119], v[176:191]
	v_add_f32_e32 v171, v80, v81
	v_permlane32_swap_b32_e32 v128, v130
	v_mfma_f32_32x32x16_bf16 v[192:207], v[244:247], v[116:119], v[192:207]
	ds_read_b128 v[252:255], v248 offset:0
	ds_read_b128 v[240:243], v160 offset:40960
	ds_read_b128 v[244:247], v160 offset:45056
	v_add_f32_e32 v171, v82, v171
	v_permlane32_swap_b32_e32 v129, v131
	v_add_f32_e32 v171, v83, v171
	s_waitcnt lgkmcnt(9)
	v_mfma_f32_32x32x16_bf16 v[176:191], v[224:227], v[120:123], v[176:191]
	v_permlane32_swap_b32_e32 v132, v134
	v_add_f32_e32 v171, v84, v171
	v_permlane32_swap_b32_e32 v133, v135
	v_mfma_f32_32x32x16_bf16 v[192:207], v[228:231], v[120:123], v[192:207]
	ds_read_b128 v[144:147], v248 offset:1024
	ds_read_b128 v[224:227], v161 offset:40960
	ds_read_b128 v[228:231], v161 offset:45056
	v_add_f32_e32 v171, v85, v171
	v_add_f32_e32 v171, v86, v171
	s_waitcnt lgkmcnt(10)
; #define SBAR() __builtin_amdgcn_sched_barrier(0)
; __device__ __forceinline__ void partialSM(f32x16& p0, f32x16& p1, float& m_reg, float& alpha, const float C, const float THRS) {
;   float pmax = p0[0];
; #pragma unroll
;   for (int r = 1; r < 16; ++r) pmax = fmaxf(pmax, p0[r]);
; #pragma unroll
;   for (int r = 0; r < 16; ++r) pmax = fmaxf(pmax, p1[r]);
;   { auto rr = __builtin_amdgcn_permlane32_swap(__float_as_uint(pmax), __float_as_uint(pmax), false, false);
;     pmax = fmaxf(__uint_as_float(rr[0]), __uint_as_float(rr[1])); }
;   float mn;
;   if (__builtin_expect(__all(pmax - m_reg <= THRS), 1)) { mn = m_reg; alpha = 1.f; }
;   else { mn = fmaxf(m_reg, pmax); alpha = __builtin_amdgcn_exp2f((m_reg - mn) * C); m_reg = mn; }
; template <int OFF> __device__ __forceinline__ s16x4 tr_read(int vb) {
;   s16x4 r; asm volatile("ds_read_b64_tr_b16 %0, %1 offset:%2" : "=&v"(r) : "v"(vb), "i"(OFF) : "memory"); return r;
; }
; template <int D0, int NCB> __device__ __forceinline__ void pv_one(f32x16& od, int vb, bf16x8 pa0, bf16x8 pa1, bf16x8 pa2, bf16x8 pa3) {
;   const s16x4 l0 = tr_read<v_rd_off<NCB>(D0, 0, 0)>(vb), h0 = tr_read<v_rd_off<NCB>(D0, 0, 1)>(vb), l1 = tr_read<v_rd_off<NCB>(D0, 1, 0)>(vb), h1 = tr_read<v_rd_off<NCB>(D0, 1, 1)>(vb);
;   const s16x4 l2 = tr_read<v_rd_off<NCB>(D0, 2, 0)>(vb), h2 = tr_read<v_rd_off<NCB>(D0, 2, 1)>(vb), l3 = tr_read<v_rd_off<NCB>(D0, 3, 0)>(vb), h3 = tr_read<v_rd_off<NCB>(D0, 3, 1)>(vb);
;   asm volatile("s_waitcnt lgkmcnt(0)" ::: "memory"); SBAR();
;     ...
;   od = __builtin_amdgcn_mfma_f32_32x32x16_bf16(pa0, PK(l0, h0), od, 0, 0, 0);
;   od = __builtin_amdgcn_mfma_f32_32x32x16_bf16(pa1, PK(l1, h1), od, 0, 0, 0);
;   od = __builtin_amdgcn_mfma_f32_32x32x16_bf16(pa2, PK(l2, h2), od, 0, 0, 0);
;   od = __builtin_amdgcn_mfma_f32_32x32x16_bf16(pa3, PK(l3, h3), od, 0, 0, 0);
;     ...
; }
; template <int NCB> __device__ __forceinline__ void pv_all(f32x16* o, int vb, bf16x8 pa0, bf16x8 pa1, bf16x8 pa2, bf16x8 pa3) {
;   pv_one<0, NCB>(o[0], vb, pa0, pa1, pa2, pa3); pv_one<1, NCB>(o[1], vb, pa0, pa1, pa2, pa3);
;   if constexpr (NCB == 4) { pv_one<2, NCB>(o[2], vb, pa0, pa1, pa2, pa3); pv_one<3, NCB>(o[3], vb, pa0, pa1, pa2, pa3); }
; }
	v_mfma_f32_32x32x16_bf16 v[176:191], v[232:235], v[124:127], v[176:191]
	v_add_f32_e32 v171, v87, v171
	v_add_f32_e32 v171, v88, v171
	ds_read_b64_tr_b16 v[72:73], v164 offset:8192
	ds_read_b64_tr_b16 v[74:75], v164 offset:10240
	ds_read_b64_tr_b16 v[76:77], v164 offset:12288
	ds_read_b64_tr_b16 v[78:79], v164 offset:14336
	v_mfma_f32_32x32x16_bf16 v[192:207], v[236:239], v[124:127], v[192:207]
	ds_read_b128 v[148:151], v248 offset:2048
	ds_read_b128 v[232:235], v162 offset:40960
	ds_read_b128 v[236:239], v162 offset:45056
	v_add_f32_e32 v171, v89, v171
	v_cvt_pk_bf16_f32 v136, v80, v81
	s_waitcnt lgkmcnt(10)
	v_mfma_f32_32x32x16_bf16 v[176:191], v[240:243], v[252:255], v[176:191]
	v_add_f32_e32 v171, v90, v171
	v_cvt_pk_bf16_f32 v137, v82, v83
	v_add_f32_e32 v171, v91, v171
	v_mfma_f32_32x32x16_bf16 v[192:207], v[244:247], v[252:255], v[192:207]
	ds_read_b128 v[252:255], v248 offset:3072
	ds_read_b128 v[240:243], v163 offset:40960
	ds_read_b128 v[244:247], v163 offset:45056
	v_cvt_pk_bf16_f32 v138, v84, v85
	v_add_f32_e32 v171, v92, v171
	s_waitcnt lgkmcnt(10)
	v_mfma_f32_32x32x16_bf16 v[176:191], v[224:227], v[144:147], v[176:191]
	v_cvt_pk_bf16_f32 v139, v86, v87
	v_add_f32_e32 v171, v93, v171
	v_cvt_pk_bf16_f32 v140, v88, v89
	v_mfma_f32_32x32x16_bf16 v[192:207], v[228:231], v[144:147], v[192:207]
	v_add_f32_e32 v171, v94, v171
	v_cvt_pk_bf16_f32 v141, v90, v91
	s_waitcnt lgkmcnt(3)
	v_mfma_f32_32x32x16_bf16 v[176:191], v[232:235], v[148:151], v[176:191]
	v_add_f32_e32 v171, v95, v171
	v_cvt_pk_bf16_f32 v142, v92, v93
	v_add_f32_e32 v170, v171, v170
	v_mfma_f32_32x32x16_bf16 v[192:207], v[236:239], v[148:151], v[192:207]
	v_cvt_pk_bf16_f32 v143, v94, v95
	s_nop 0
	s_waitcnt lgkmcnt(0)
	v_mfma_f32_32x32x16_bf16 v[176:191], v[240:243], v[252:255], v[176:191]
	v_permlane32_swap_b32_e32 v136, v138
	v_permlane32_swap_b32_e32 v137, v139
	v_permlane32_swap_b32_e32 v140, v142
	v_mfma_f32_32x32x16_bf16 v[192:207], v[244:247], v[252:255], v[192:207]
	v_permlane32_swap_b32_e32 v141, v143
	ds_read_b64_tr_b16 v[80:81], v164 offset:512
	ds_read_b64_tr_b16 v[82:83], v164 offset:2560
	ds_read_b64_tr_b16 v[84:85], v164 offset:4608
	ds_read_b64_tr_b16 v[86:87], v164 offset:6656
	ds_read_b64_tr_b16 v[88:89], v164 offset:8704
	ds_read_b64_tr_b16 v[90:91], v164 offset:10752
	ds_read_b64_tr_b16 v[92:93], v164 offset:12800
	ds_read_b64_tr_b16 v[94:95], v164 offset:14848
	s_waitcnt lgkmcnt(14)
	v_mfma_f32_32x32x16_bf16 v[0:15], v[128:131], v[64:67], v[0:15]
	v_mfma_f32_32x32x16_bf16 v[0:15], v[132:135], v[68:71], v[0:15]
	ds_read_b64_tr_b16 v[64:65], v164 offset:1024
	ds_read_b64_tr_b16 v[66:67], v164 offset:3072
	ds_read_b64_tr_b16 v[68:69], v164 offset:5120
	ds_read_b64_tr_b16 v[70:71], v164 offset:7168
	v_mfma_f32_32x32x16_bf16 v[0:15], v[136:139], v[72:75], v[0:15]
	v_mfma_f32_32x32x16_bf16 v[0:15], v[140:143], v[76:79], v[0:15]
	ds_read_b64_tr_b16 v[72:73], v164 offset:9216
	ds_read_b64_tr_b16 v[74:75], v164 offset:11264
	ds_read_b64_tr_b16 v[76:77], v164 offset:13312
	ds_read_b64_tr_b16 v[78:79], v164 offset:15360
	s_waitcnt lgkmcnt(8)
	v_mfma_f32_32x32x16_bf16 v[48:63], v[128:131], v[80:83], v[48:63]
	v_max3_f32 v224, v176, v177, v178
	v_max3_f32 v225, v192, v193, v194
	v_max3_f32 v224, v224, v179, v180
	v_max3_f32 v225, v225, v195, v196
	v_max3_f32 v224, v224, v181, v182
	v_mfma_f32_32x32x16_bf16 v[48:63], v[132:135], v[84:87], v[48:63]
	v_max3_f32 v225, v225, v197, v198
	v_max3_f32 v224, v224, v183, v184
	v_max3_f32 v225, v225, v199, v200
	v_max3_f32 v224, v224, v185, v186
	v_max3_f32 v225, v225, v201, v202
	ds_read_b64_tr_b16 v[80:81], v164 offset:1536
	ds_read_b64_tr_b16 v[82:83], v164 offset:3584
	ds_read_b64_tr_b16 v[84:85], v164 offset:5632
	ds_read_b64_tr_b16 v[86:87], v164 offset:7680
	v_mfma_f32_32x32x16_bf16 v[48:63], v[136:139], v[88:91], v[48:63]
	v_max3_f32 v224, v224, v187, v188
	v_max3_f32 v225, v225, v203, v204
	v_max3_f32 v224, v224, v189, v190
	v_max3_f32 v225, v225, v205, v206
	v_max_f32_e32 v224, v191, v224
	v_mfma_f32_32x32x16_bf16 v[48:63], v[140:143], v[92:95], v[48:63]
	v_max_f32_e32 v225, v207, v225
	v_max_f32_e32 v226, v224, v225
	v_mov_b32_e32 v227, v226
	s_nop 1
	v_permlane32_swap_b32_e32 v226, v227
	v_max_f32_e32 v226, v226, v227
	ds_read_b64_tr_b16 v[88:89], v164 offset:9728
	ds_read_b64_tr_b16 v[90:91], v164 offset:11776
	ds_read_b64_tr_b16 v[92:93], v164 offset:13824
	ds_read_b64_tr_b16 v[94:95], v164 offset:15872
	s_waitcnt lgkmcnt(8)
	v_mfma_f32_32x32x16_bf16 v[32:47], v[128:131], v[64:67], v[32:47]
	v_cmp_lt_f32_e32 vcc, 0x4138aa3b, v226
	s_cbranch_vccnz .Lat_r1_s1

; #define SBAR() __builtin_amdgcn_sched_barrier(0)
; #define WAITV() asm volatile("s_waitcnt vmcnt(0)" ::: "memory")
; __device__ __forceinline__ void finishSM(f32x16& p0, f32x16& p1, float alpha, float& l_reg, bf16x8& pa0, bf16x8& pa1, bf16x8& pa2, bf16x8& pa3) {
; #pragma unroll
;   for (int r = 0; r < 16; ++r) p1[r] = __builtin_amdgcn_exp2f(p1[r]);
;   float ps = 0;
; #pragma unroll
;   for (int r = 0; r < 16; ++r) ps += p0[r];
; #pragma unroll
;   for (int r = 0; r < 16; ++r) ps += p1[r];
;   { auto rr = __builtin_amdgcn_permlane32_swap(__float_as_uint(ps), __float_as_uint(ps), false, false);
;     ps = __uint_as_float(rr[0]) + __uint_as_float(rr[1]); }
;   l_reg = l_reg * alpha + ps;
;     ...
;   PK4(p0, 0, pa0); PK4(p0, 8, pa1); PK4(p1, 0, pa2); PK4(p1, 8, pa3);
;     ...
; }
; template <int DN>
; __device__ __forceinline__ void qkt(f32x16& p0, f32x16& p1, const char* Kn, const char* Kr, const bf16x8* qr, const char* qrl, int r32, int hi) {
;   p0 = f32x16{}; p1 = f32x16{};
;   if constexpr (DN > 0) {
; #pragma unroll
;     for (int d0 = 0; d0 < DN / 16; ++d0) { const int cb = (d0 * 16 + hi * 8) * 2;
;       bf16x8 b0 = *reinterpret_cast<const bf16x8*>(Kn + KSWZ(r32, cb));
;       bf16x8 b1 = *reinterpret_cast<const bf16x8*>(Kn + KSWZ(32 + r32, cb));
;       p0 = __builtin_amdgcn_mfma_f32_32x32x16_bf16(b0, qr[d0], p0, 0, 0, 0);
;       p1 = __builtin_amdgcn_mfma_f32_32x32x16_bf16(b1, qr[d0], p1, 0, 0, 0); }
;   }
; #pragma unroll
;   for (int d0 = 0; d0 < 4; ++d0) { const int cb = (d0 * 16 + hi * 8) * 2;
;     bf16x8 b0 = *reinterpret_cast<const bf16x8*>(Kr + KSWZ64(r32, cb));
;     bf16x8 b1 = *reinterpret_cast<const bf16x8*>(Kr + KSWZ64(32 + r32, cb));
;     bf16x8 q; if constexpr (DN > 0) q = *reinterpret_cast<const bf16x8*>(qrl + d0 * 1024); else q = qr[d0];
;     p0 = __builtin_amdgcn_mfma_f32_32x32x16_bf16(b0, q, p0, 0, 0, 0);
;     p1 = __builtin_amdgcn_mfma_f32_32x32x16_bf16(b1, q, p1, 0, 0, 0); }
; }
; template <int DN, int DV, bool MASK> ...
;     ...
;   for (int j = 1; j + 1 < NT; j += 2) {
;     DMA(j + 1, bn);
;     nB = NEED(j);
;     SBAR(); if (nB) SCORE(pB0, pB1, bc, j);
;     if (nA) finishSM(pA0, pA1, alA, l_reg, pa0, pa1, pa2, pa3); SBAR();
;     if (nA) pv_all<NCB>(o, vb0 + bp, pa0, pa1, pa2, pa3);
;     if (nB) { partialSM(pB0, pB1, m_reg, alB, C, THRS); RESC(alB); }
;     WAITV(); __syncthreads(); ROT();
.Lat_loop:
	ds_read_b128 v[224:227], v152 offset:0
	ds_read_b128 v[228:231], v152 offset:8192
	ds_read_b128 v[232:235], v153 offset:0
	ds_read_b128 v[236:239], v153 offset:8192
	ds_read_b128 v[240:243], v154 offset:0
	ds_read_b128 v[244:247], v154 offset:8192
	v_mfma_f32_32x32x16_bf16 v[16:31], v[128:131], v[80:83], v[16:31]
	s_add_i32 m0, s82, 49152
	v_exp_f32_e32 v192, v192
	global_load_lds_dwordx4 v165, s[4:5]
	v_exp_f32_e32 v193, v193
	s_add_i32 m0, s82, 50176
	v_exp_f32_e32 v194, v194
	global_load_lds_dwordx4 v169, s[4:5]
	v_mfma_f32_32x32x16_bf16 v[16:31], v[132:135], v[84:87], v[16:31]
	v_exp_f32_e32 v195, v195
	s_add_i32 m0, s82, 24576
	v_exp_f32_e32 v196, v196
	global_load_lds_dwordx4 v166, s[6:7]
	v_exp_f32_e32 v197, v197
	s_add_i32 m0, s82, 25600
	v_exp_f32_e32 v198, v198
	global_load_lds_dwordx4 v167, s[6:7]
	v_mfma_f32_32x32x16_bf16 v[16:31], v[136:139], v[88:91], v[16:31]
	v_exp_f32_e32 v199, v199
	s_add_i32 m0, s83, 40960
	v_exp_f32_e32 v200, v200
	global_load_lds_dwordx4 v168, s[8:9]
	v_exp_f32_e32 v201, v201
	s_mov_b64 s[4:5], s[6:7]
	v_exp_f32_e32 v202, v202
	s_add_u32 s6, s6, 0x80000
	v_mfma_f32_32x32x16_bf16 v[16:31], v[140:143], v[92:95], v[16:31]
	v_exp_f32_e32 v203, v203
	s_addc_u32 s7, s7, 0
	v_exp_f32_e32 v204, v204
	s_add_u32 s8, s8, 0x2000
	v_exp_f32_e32 v205, v205
	s_addc_u32 s9, s9, 0
	v_exp_f32_e32 v206, v206
	v_exp_f32_e32 v207, v207
	s_cmp_lg_u32 s10, 0
	s_cbranch_scc1 .Lat_r2_la
.Lat_r2ret_la:
	s_waitcnt lgkmcnt(4)
	v_mfma_f32_32x32x16_bf16 v[64:79], v[224:227], v[96:99], v[208:223]
	v_add_f32_e32 v170, v176, v170
	v_cvt_pk_bf16_f32 v128, v176, v177
	v_mfma_f32_32x32x16_bf16 v[80:95], v[228:231], v[96:99], v[208:223]
	ds_read_b128 v[224:227], v155 offset:0
	ds_read_b128 v[228:231], v155 offset:8192
	v_add_f32_e32 v170, v177, v170
	v_cvt_pk_bf16_f32 v129, v178, v179
	v_add_f32_e32 v170, v178, v170
	s_waitcnt lgkmcnt(4)
	v_mfma_f32_32x32x16_bf16 v[64:79], v[232:235], v[100:103], v[64:79]
	v_cvt_pk_bf16_f32 v130, v180, v181
	v_add_f32_e32 v170, v179, v170
	v_mfma_f32_32x32x16_bf16 v[80:95], v[236:239], v[100:103], v[80:95]
	ds_read_b128 v[232:235], v156 offset:0
	ds_read_b128 v[236:239], v156 offset:8192
	v_cvt_pk_bf16_f32 v131, v182, v183
	v_add_f32_e32 v170, v180, v170
	v_add_f32_e32 v170, v181, v170
	s_waitcnt lgkmcnt(4)
	v_mfma_f32_32x32x16_bf16 v[64:79], v[240:243], v[104:107], v[64:79]
	v_add_f32_e32 v170, v182, v170
	v_add_f32_e32 v170, v183, v170
	v_mfma_f32_32x32x16_bf16 v[80:95], v[244:247], v[104:107], v[80:95]
	ds_read_b128 v[240:243], v157 offset:0
	ds_read_b128 v[244:247], v157 offset:8192
	v_add_f32_e32 v170, v184, v170
	v_cvt_pk_bf16_f32 v132, v184, v185
	v_add_f32_e32 v170, v185, v170
	s_waitcnt lgkmcnt(4)
	v_mfma_f32_32x32x16_bf16 v[64:79], v[224:227], v[108:111], v[64:79]
	v_cvt_pk_bf16_f32 v133, v186, v187
	v_add_f32_e32 v170, v186, v170
	v_mfma_f32_32x32x16_bf16 v[80:95], v[228:231], v[108:111], v[80:95]
	ds_read_b128 v[224:227], v158 offset:0
	ds_read_b128 v[228:231], v158 offset:8192
	v_cvt_pk_bf16_f32 v134, v188, v189
	v_add_f32_e32 v170, v187, v170
	v_cvt_pk_bf16_f32 v135, v190, v191
	s_waitcnt lgkmcnt(4)
	v_mfma_f32_32x32x16_bf16 v[64:79], v[232:235], v[112:115], v[64:79]
	v_add_f32_e32 v170, v188, v170
	v_add_f32_e32 v170, v189, v170
	v_mfma_f32_32x32x16_bf16 v[80:95], v[236:239], v[112:115], v[80:95]
	ds_read_b128 v[232:235], v159 offset:0
	ds_read_b128 v[236:239], v159 offset:8192
	v_add_f32_e32 v170, v190, v170
	v_add_f32_e32 v170, v191, v170
	ds_read_b64_tr_b16 v[176:177], v164 offset:16384
	ds_read_b64_tr_b16 v[178:179], v164 offset:18432
	ds_read_b64_tr_b16 v[180:181], v164 offset:20480
	ds_read_b64_tr_b16 v[182:183], v164 offset:22528
	s_waitcnt lgkmcnt(8)
	v_mfma_f32_32x32x16_bf16 v[64:79], v[240:243], v[116:119], v[64:79]
	v_add_f32_e32 v171, v192, v193
	v_permlane32_swap_b32_e32 v128, v130
	v_mfma_f32_32x32x16_bf16 v[80:95], v[244:247], v[116:119], v[80:95]
	ds_read_b128 v[252:255], v248 offset:0
	ds_read_b128 v[240:243], v160 offset:16384
	ds_read_b128 v[244:247], v160 offset:20480
	v_add_f32_e32 v171, v194, v171
	v_permlane32_swap_b32_e32 v129, v131
	v_add_f32_e32 v171, v195, v171
	s_waitcnt lgkmcnt(9)
	v_mfma_f32_32x32x16_bf16 v[64:79], v[224:227], v[120:123], v[64:79]
	v_permlane32_swap_b32_e32 v132, v134
	v_add_f32_e32 v171, v196, v171
	v_permlane32_swap_b32_e32 v133, v135
	v_mfma_f32_32x32x16_bf16 v[80:95], v[228:231], v[120:123], v[80:95]
	ds_read_b128 v[144:147], v248 offset:1024
	ds_read_b128 v[224:227], v161 offset:16384
	ds_read_b128 v[228:231], v161 offset:20480
	v_add_f32_e32 v171, v197, v171
	v_add_f32_e32 v171, v198, v171
	s_waitcnt lgkmcnt(10)
	v_mfma_f32_32x32x16_bf16 v[64:79], v[232:235], v[124:127], v[64:79]
	v_add_f32_e32 v171, v199, v171
	v_add_f32_e32 v171, v200, v171
	ds_read_b64_tr_b16 v[184:185], v164 offset:24576
	ds_read_b64_tr_b16 v[186:187], v164 offset:26624
	ds_read_b64_tr_b16 v[188:189], v164 offset:28672
	ds_read_b64_tr_b16 v[190:191], v164 offset:30720
	v_mfma_f32_32x32x16_bf16 v[80:95], v[236:239], v[124:127], v[80:95]
	ds_read_b128 v[148:151], v248 offset:2048
	ds_read_b128 v[232:235], v162 offset:16384
	ds_read_b128 v[236:239], v162 offset:20480
	v_add_f32_e32 v171, v201, v171
	v_cvt_pk_bf16_f32 v136, v192, v193
	s_waitcnt lgkmcnt(10)
	v_mfma_f32_32x32x16_bf16 v[64:79], v[240:243], v[252:255], v[64:79]
	v_add_f32_e32 v171, v202, v171
	v_cvt_pk_bf16_f32 v137, v194, v195
	v_add_f32_e32 v171, v203, v171
	v_mfma_f32_32x32x16_bf16 v[80:95], v[244:247], v[252:255], v[80:95]
	ds_read_b128 v[252:255], v248 offset:3072
	ds_read_b128 v[240:243], v163 offset:16384
	ds_read_b128 v[244:247], v163 offset:20480
	v_cvt_pk_bf16_f32 v138, v196, v197
	v_add_f32_e32 v171, v204, v171
	s_waitcnt lgkmcnt(10)
; #define SBAR() __builtin_amdgcn_sched_barrier(0)
; #define WAITV() asm volatile("s_waitcnt vmcnt(0)" ::: "memory")
; #define NEED(j) (!MASK || (j) < n1 || (KP(j) <= q0w + 159 && KP(j) + 63 >= q0w - 128))
; #define SCORE(P0, P1, b, j) do { qkt<DN>(P0, P1, Knl + (b), Krl + (b), qr, qrl, r32, hi); \
;     if constexpr (MASK) { if ((j) >= n1 && !(KP(j) >= q0w - 97 && KP(j) <= q0w + 65)) band_mask(P0, P1, qd - KP(j)); } } while (0)
; #define ROT() do { const int t_ = bp; bp = bc; bc = bn; bn = t_; } while (0)
; template <int OFF> __device__ __forceinline__ s16x4 tr_read(int vb) {
;   s16x4 r; asm volatile("ds_read_b64_tr_b16 %0, %1 offset:%2" : "=&v"(r) : "v"(vb), "i"(OFF) : "memory"); return r;
; }
; template <int D0, int NCB> __device__ __forceinline__ void pv_one(f32x16& od, int vb, bf16x8 pa0, bf16x8 pa1, bf16x8 pa2, bf16x8 pa3) {
;   const s16x4 l0 = tr_read<v_rd_off<NCB>(D0, 0, 0)>(vb), h0 = tr_read<v_rd_off<NCB>(D0, 0, 1)>(vb), l1 = tr_read<v_rd_off<NCB>(D0, 1, 0)>(vb), h1 = tr_read<v_rd_off<NCB>(D0, 1, 1)>(vb);
;   const s16x4 l2 = tr_read<v_rd_off<NCB>(D0, 2, 0)>(vb), h2 = tr_read<v_rd_off<NCB>(D0, 2, 1)>(vb), l3 = tr_read<v_rd_off<NCB>(D0, 3, 0)>(vb), h3 = tr_read<v_rd_off<NCB>(D0, 3, 1)>(vb);
;   asm volatile("s_waitcnt lgkmcnt(0)" ::: "memory"); SBAR();
;     ...
;   od = __builtin_amdgcn_mfma_f32_32x32x16_bf16(pa0, PK(l0, h0), od, 0, 0, 0);
;   od = __builtin_amdgcn_mfma_f32_32x32x16_bf16(pa1, PK(l1, h1), od, 0, 0, 0);
;   od = __builtin_amdgcn_mfma_f32_32x32x16_bf16(pa2, PK(l2, h2), od, 0, 0, 0);
;   od = __builtin_amdgcn_mfma_f32_32x32x16_bf16(pa3, PK(l3, h3), od, 0, 0, 0);
;     ...
; }
; template <int NCB> __device__ __forceinline__ void pv_all(f32x16* o, int vb, bf16x8 pa0, bf16x8 pa1, bf16x8 pa2, bf16x8 pa3) {
;   pv_one<0, NCB>(o[0], vb, pa0, pa1, pa2, pa3); pv_one<1, NCB>(o[1], vb, pa0, pa1, pa2, pa3);
;   if constexpr (NCB == 4) { pv_one<2, NCB>(o[2], vb, pa0, pa1, pa2, pa3); pv_one<3, NCB>(o[3], vb, pa0, pa1, pa2, pa3); }
; }
; template <int DN, int DV, bool MASK> ...
;     ...
;     WAITV(); __syncthreads(); ROT();
;     DMA(j + 2, bn);
;     nA = NEED(j + 1);
;     SBAR(); if (nA) SCORE(pA0, pA1, bc, j + 1);
	v_mfma_f32_32x32x16_bf16 v[64:79], v[224:227], v[144:147], v[64:79]
	v_cvt_pk_bf16_f32 v139, v198, v199
	v_add_f32_e32 v171, v205, v171
	v_cvt_pk_bf16_f32 v140, v200, v201
	v_mfma_f32_32x32x16_bf16 v[80:95], v[228:231], v[144:147], v[80:95]
	v_add_f32_e32 v171, v206, v171
	v_cvt_pk_bf16_f32 v141, v202, v203
	s_waitcnt lgkmcnt(3)
	v_mfma_f32_32x32x16_bf16 v[64:79], v[232:235], v[148:151], v[64:79]
	v_add_f32_e32 v171, v207, v171
	v_cvt_pk_bf16_f32 v142, v204, v205
	v_add_f32_e32 v170, v171, v170
	v_mfma_f32_32x32x16_bf16 v[80:95], v[236:239], v[148:151], v[80:95]
	v_cvt_pk_bf16_f32 v143, v206, v207
	s_nop 0
	s_waitcnt lgkmcnt(0)
	v_mfma_f32_32x32x16_bf16 v[64:79], v[240:243], v[252:255], v[64:79]
	v_permlane32_swap_b32_e32 v136, v138
	v_permlane32_swap_b32_e32 v137, v139
	v_permlane32_swap_b32_e32 v140, v142
	v_mfma_f32_32x32x16_bf16 v[80:95], v[244:247], v[252:255], v[80:95]
	v_permlane32_swap_b32_e32 v141, v143
	ds_read_b64_tr_b16 v[192:193], v164 offset:16896
	ds_read_b64_tr_b16 v[194:195], v164 offset:18944
	ds_read_b64_tr_b16 v[196:197], v164 offset:20992
	ds_read_b64_tr_b16 v[198:199], v164 offset:23040
	ds_read_b64_tr_b16 v[200:201], v164 offset:25088
	ds_read_b64_tr_b16 v[202:203], v164 offset:27136
	ds_read_b64_tr_b16 v[204:205], v164 offset:29184
	ds_read_b64_tr_b16 v[206:207], v164 offset:31232
	s_waitcnt lgkmcnt(14)
	v_mfma_f32_32x32x16_bf16 v[0:15], v[128:131], v[176:179], v[0:15]
	v_mfma_f32_32x32x16_bf16 v[0:15], v[132:135], v[180:183], v[0:15]
	ds_read_b64_tr_b16 v[176:177], v164 offset:17408
	ds_read_b64_tr_b16 v[178:179], v164 offset:19456
	ds_read_b64_tr_b16 v[180:181], v164 offset:21504
	ds_read_b64_tr_b16 v[182:183], v164 offset:23552
	v_mfma_f32_32x32x16_bf16 v[0:15], v[136:139], v[184:187], v[0:15]
	v_mfma_f32_32x32x16_bf16 v[0:15], v[140:143], v[188:191], v[0:15]
	ds_read_b64_tr_b16 v[184:185], v164 offset:25600
	ds_read_b64_tr_b16 v[186:187], v164 offset:27648
	ds_read_b64_tr_b16 v[188:189], v164 offset:29696
	ds_read_b64_tr_b16 v[190:191], v164 offset:31744
	s_waitcnt lgkmcnt(8)
	v_mfma_f32_32x32x16_bf16 v[48:63], v[128:131], v[192:195], v[48:63]
	v_max3_f32 v224, v64, v65, v66
	v_max3_f32 v225, v80, v81, v82
	v_max3_f32 v224, v224, v67, v68
	v_max3_f32 v225, v225, v83, v84
	v_max3_f32 v224, v224, v69, v70
	v_mfma_f32_32x32x16_bf16 v[48:63], v[132:135], v[196:199], v[48:63]
	v_max3_f32 v225, v225, v85, v86
	v_max3_f32 v224, v224, v71, v72
	v_max3_f32 v225, v225, v87, v88
	v_max3_f32 v224, v224, v73, v74
	v_max3_f32 v225, v225, v89, v90
	ds_read_b64_tr_b16 v[192:193], v164 offset:17920
	ds_read_b64_tr_b16 v[194:195], v164 offset:19968
	ds_read_b64_tr_b16 v[196:197], v164 offset:22016
	ds_read_b64_tr_b16 v[198:199], v164 offset:24064
	v_mfma_f32_32x32x16_bf16 v[48:63], v[136:139], v[200:203], v[48:63]
	v_max3_f32 v224, v224, v75, v76
	v_max3_f32 v225, v225, v91, v92
	v_max3_f32 v224, v224, v77, v78
	v_max3_f32 v225, v225, v93, v94
	v_max_f32_e32 v224, v79, v224
	v_mfma_f32_32x32x16_bf16 v[48:63], v[140:143], v[204:207], v[48:63]
	v_max_f32_e32 v225, v95, v225
	v_max_f32_e32 v226, v224, v225
	v_mov_b32_e32 v227, v226
	s_nop 1
	v_permlane32_swap_b32_e32 v226, v227
	v_max_f32_e32 v226, v226, v227
	ds_read_b64_tr_b16 v[200:201], v164 offset:26112
	ds_read_b64_tr_b16 v[202:203], v164 offset:28160
	ds_read_b64_tr_b16 v[204:205], v164 offset:30208
	ds_read_b64_tr_b16 v[206:207], v164 offset:32256
	s_waitcnt lgkmcnt(8)
	v_mfma_f32_32x32x16_bf16 v[32:47], v[128:131], v[176:179], v[32:47]
	v_cmp_lt_f32_e32 vcc, 0x4138aa3b, v226
	s_cbranch_vccnz .Lat_r1_la
.Lat_r1ret_la:
	v_exp_f32_e32 v64, v64
	v_exp_f32_e32 v65, v65
	v_exp_f32_e32 v66, v66
	v_mfma_f32_32x32x16_bf16 v[32:47], v[132:135], v[180:183], v[32:47]
	v_exp_f32_e32 v67, v67
	v_exp_f32_e32 v68, v68
	v_exp_f32_e32 v69, v69
	v_exp_f32_e32 v70, v70
	v_mfma_f32_32x32x16_bf16 v[32:47], v[136:139], v[184:187], v[32:47]
	v_exp_f32_e32 v71, v71
	v_exp_f32_e32 v72, v72
	v_exp_f32_e32 v73, v73
	v_exp_f32_e32 v74, v74
	v_mfma_f32_32x32x16_bf16 v[32:47], v[140:143], v[188:191], v[32:47]
	v_exp_f32_e32 v75, v75
	v_exp_f32_e32 v76, v76
	v_exp_f32_e32 v77, v77
	v_exp_f32_e32 v78, v78
	v_exp_f32_e32 v79, v79
	s_waitcnt vmcnt(0) lgkmcnt(0)
	s_barrier
	ds_read_b128 v[224:227], v152 offset:24576
	ds_read_b128 v[228:231], v152 offset:32768
	ds_read_b128 v[232:235], v153 offset:24576
	ds_read_b128 v[236:239], v153 offset:32768
	ds_read_b128 v[240:243], v154 offset:24576
	ds_read_b128 v[244:247], v154 offset:32768
	v_mfma_f32_32x32x16_bf16 v[16:31], v[128:131], v[192:195], v[16:31]
	s_add_i32 m0, s82, 65536
	v_exp_f32_e32 v80, v80
	global_load_lds_dwordx4 v165, s[4:5]
	v_exp_f32_e32 v81, v81
	s_add_i32 m0, s82, 66560
	v_exp_f32_e32 v82, v82
	global_load_lds_dwordx4 v169, s[4:5]
	v_mfma_f32_32x32x16_bf16 v[16:31], v[132:135], v[196:199], v[16:31]
	v_exp_f32_e32 v83, v83
	s_add_i32 m0, s82, 0
	v_exp_f32_e32 v84, v84
	global_load_lds_dwordx4 v166, s[6:7]
	v_exp_f32_e32 v85, v85
	s_add_i32 m0, s82, 1024
	v_exp_f32_e32 v86, v86
	global_load_lds_dwordx4 v167, s[6:7]
	v_mfma_f32_32x32x16_bf16 v[16:31], v[136:139], v[200:203], v[16:31]
	v_exp_f32_e32 v87, v87
	s_add_i32 m0, s83, 16384
	v_exp_f32_e32 v88, v88
	global_load_lds_dwordx4 v168, s[8:9]
	v_exp_f32_e32 v89, v89
	s_mov_b64 s[4:5], s[6:7]
	v_exp_f32_e32 v90, v90
	s_add_u32 s6, s6, 0x80000
	v_mfma_f32_32x32x16_bf16 v[16:31], v[140:143], v[204:207], v[16:31]
	v_exp_f32_e32 v91, v91
	s_addc_u32 s7, s7, 0
	v_exp_f32_e32 v92, v92
	s_add_u32 s8, s8, 0x2000
	v_exp_f32_e32 v93, v93
	s_addc_u32 s9, s9, 0
	v_exp_f32_e32 v94, v94
	v_exp_f32_e32 v95, v95
	s_cmp_lg_u32 s10, 0
	s_cbranch_scc1 .Lat_r2_lb
; __device__ __forceinline__ void finishSM(f32x16& p0, f32x16& p1, float alpha, float& l_reg, bf16x8& pa0, bf16x8& pa1, bf16x8& pa2, bf16x8& pa3) {
; #pragma unroll
;   for (int r = 0; r < 16; ++r) p1[r] = __builtin_amdgcn_exp2f(p1[r]);
;   float ps = 0;
; #pragma unroll
;   for (int r = 0; r < 16; ++r) ps += p0[r];
; #pragma unroll
;   for (int r = 0; r < 16; ++r) ps += p1[r];
;   { auto rr = __builtin_amdgcn_permlane32_swap(__float_as_uint(ps), __float_as_uint(ps), false, false);
;     ps = __uint_as_float(rr[0]) + __uint_as_float(rr[1]); }
;   l_reg = l_reg * alpha + ps;
;     ...
;   PK4(p0, 0, pa0); PK4(p0, 8, pa1); PK4(p1, 0, pa2); PK4(p1, 8, pa3);
;     ...
; }
; template <int DN>
; __device__ __forceinline__ void qkt(f32x16& p0, f32x16& p1, const char* Kn, const char* Kr, const bf16x8* qr, const char* qrl, int r32, int hi) {
;   p0 = f32x16{}; p1 = f32x16{};
;   if constexpr (DN > 0) {
; #pragma unroll
;     for (int d0 = 0; d0 < DN / 16; ++d0) { const int cb = (d0 * 16 + hi * 8) * 2;
;       bf16x8 b0 = *reinterpret_cast<const bf16x8*>(Kn + KSWZ(r32, cb));
;       bf16x8 b1 = *reinterpret_cast<const bf16x8*>(Kn + KSWZ(32 + r32, cb));
;       p0 = __builtin_amdgcn_mfma_f32_32x32x16_bf16(b0, qr[d0], p0, 0, 0, 0);
;       p1 = __builtin_amdgcn_mfma_f32_32x32x16_bf16(b1, qr[d0], p1, 0, 0, 0); }
;   }
; #pragma unroll
;   for (int d0 = 0; d0 < 4; ++d0) { const int cb = (d0 * 16 + hi * 8) * 2;
;     bf16x8 b0 = *reinterpret_cast<const bf16x8*>(Kr + KSWZ64(r32, cb));
;     bf16x8 b1 = *reinterpret_cast<const bf16x8*>(Kr + KSWZ64(32 + r32, cb));
;     bf16x8 q; if constexpr (DN > 0) q = *reinterpret_cast<const bf16x8*>(qrl + d0 * 1024); else q = qr[d0];
;     p0 = __builtin_amdgcn_mfma_f32_32x32x16_bf16(b0, q, p0, 0, 0, 0);
;     p1 = __builtin_amdgcn_mfma_f32_32x32x16_bf16(b1, q, p1, 0, 0, 0); }
; }
.Lat_r2ret_lb:
	s_waitcnt lgkmcnt(4)
	v_mfma_f32_32x32x16_bf16 v[176:191], v[224:227], v[96:99], v[208:223]
	v_add_f32_e32 v170, v64, v170
	v_cvt_pk_bf16_f32 v128, v64, v65
	v_mfma_f32_32x32x16_bf16 v[192:207], v[228:231], v[96:99], v[208:223]
	ds_read_b128 v[224:227], v155 offset:24576
	ds_read_b128 v[228:231], v155 offset:32768
	v_add_f32_e32 v170, v65, v170
	v_cvt_pk_bf16_f32 v129, v66, v67
	v_add_f32_e32 v170, v66, v170
	s_waitcnt lgkmcnt(4)
	v_mfma_f32_32x32x16_bf16 v[176:191], v[232:235], v[100:103], v[176:191]
	v_cvt_pk_bf16_f32 v130, v68, v69
	v_add_f32_e32 v170, v67, v170
	v_mfma_f32_32x32x16_bf16 v[192:207], v[236:239], v[100:103], v[192:207]
	ds_read_b128 v[232:235], v156 offset:24576
	ds_read_b128 v[236:239], v156 offset:32768
	v_cvt_pk_bf16_f32 v131, v70, v71
	v_add_f32_e32 v170, v68, v170
	v_add_f32_e32 v170, v69, v170
	s_waitcnt lgkmcnt(4)
	v_mfma_f32_32x32x16_bf16 v[176:191], v[240:243], v[104:107], v[176:191]
	v_add_f32_e32 v170, v70, v170
	v_add_f32_e32 v170, v71, v170
	v_mfma_f32_32x32x16_bf16 v[192:207], v[244:247], v[104:107], v[192:207]
	ds_read_b128 v[240:243], v157 offset:24576
	ds_read_b128 v[244:247], v157 offset:32768
	v_add_f32_e32 v170, v72, v170
	v_cvt_pk_bf16_f32 v132, v72, v73
	v_add_f32_e32 v170, v73, v170
	s_waitcnt lgkmcnt(4)
	v_mfma_f32_32x32x16_bf16 v[176:191], v[224:227], v[108:111], v[176:191]
	v_cvt_pk_bf16_f32 v133, v74, v75
	v_add_f32_e32 v170, v74, v170
	v_mfma_f32_32x32x16_bf16 v[192:207], v[228:231], v[108:111], v[192:207]
	ds_read_b128 v[224:227], v158 offset:24576
	ds_read_b128 v[228:231], v158 offset:32768
	v_cvt_pk_bf16_f32 v134, v76, v77
	v_add_f32_e32 v170, v75, v170
	v_cvt_pk_bf16_f32 v135, v78, v79
	s_waitcnt lgkmcnt(4)
	v_mfma_f32_32x32x16_bf16 v[176:191], v[232:235], v[112:115], v[176:191]
	v_add_f32_e32 v170, v76, v170
	v_add_f32_e32 v170, v77, v170
	v_mfma_f32_32x32x16_bf16 v[192:207], v[236:239], v[112:115], v[192:207]
	ds_read_b128 v[232:235], v159 offset:24576
	ds_read_b128 v[236:239], v159 offset:32768
	v_add_f32_e32 v170, v78, v170
	v_add_f32_e32 v170, v79, v170
	ds_read_b64_tr_b16 v[64:65], v164 offset:0
	ds_read_b64_tr_b16 v[66:67], v164 offset:2048
	ds_read_b64_tr_b16 v[68:69], v164 offset:4096
	ds_read_b64_tr_b16 v[70:71], v164 offset:6144
	s_waitcnt lgkmcnt(8)
	v_mfma_f32_32x32x16_bf16 v[176:191], v[240:243], v[116:119], v[176:191]
	v_add_f32_e32 v171, v80, v81
	v_permlane32_swap_b32_e32 v128, v130
	v_mfma_f32_32x32x16_bf16 v[192:207], v[244:247], v[116:119], v[192:207]
	ds_read_b128 v[252:255], v248 offset:0
	ds_read_b128 v[240:243], v160 offset:40960
	ds_read_b128 v[244:247], v160 offset:45056
	v_add_f32_e32 v171, v82, v171
	v_permlane32_swap_b32_e32 v129, v131
	v_add_f32_e32 v171, v83, v171
	s_waitcnt lgkmcnt(9)
	v_mfma_f32_32x32x16_bf16 v[176:191], v[224:227], v[120:123], v[176:191]
	v_permlane32_swap_b32_e32 v132, v134
	v_add_f32_e32 v171, v84, v171
	v_permlane32_swap_b32_e32 v133, v135
	v_mfma_f32_32x32x16_bf16 v[192:207], v[228:231], v[120:123], v[192:207]
	ds_read_b128 v[144:147], v248 offset:1024
	ds_read_b128 v[224:227], v161 offset:40960
	ds_read_b128 v[228:231], v161 offset:45056
	v_add_f32_e32 v171, v85, v171
	v_add_f32_e32 v171, v86, v171
	s_waitcnt lgkmcnt(10)
	v_mfma_f32_32x32x16_bf16 v[176:191], v[232:235], v[124:127], v[176:191]
	v_add_f32_e32 v171, v87, v171
	v_add_f32_e32 v171, v88, v171
	ds_read_b64_tr_b16 v[72:73], v164 offset:8192
	ds_read_b64_tr_b16 v[74:75], v164 offset:10240
	ds_read_b64_tr_b16 v[76:77], v164 offset:12288
	ds_read_b64_tr_b16 v[78:79], v164 offset:14336
	v_mfma_f32_32x32x16_bf16 v[192:207], v[236:239], v[124:127], v[192:207]
	ds_read_b128 v[148:151], v248 offset:2048
	ds_read_b128 v[232:235], v162 offset:40960
	ds_read_b128 v[236:239], v162 offset:45056
	v_add_f32_e32 v171, v89, v171
	v_cvt_pk_bf16_f32 v136, v80, v81
	s_waitcnt lgkmcnt(10)
; #define SBAR() __builtin_amdgcn_sched_barrier(0)
; __device__ __forceinline__ void partialSM(f32x16& p0, f32x16& p1, float& m_reg, float& alpha, const float C, const float THRS) {
;   float pmax = p0[0];
; #pragma unroll
;   for (int r = 1; r < 16; ++r) pmax = fmaxf(pmax, p0[r]);
; #pragma unroll
;   for (int r = 0; r < 16; ++r) pmax = fmaxf(pmax, p1[r]);
;   { auto rr = __builtin_amdgcn_permlane32_swap(__float_as_uint(pmax), __float_as_uint(pmax), false, false);
;     pmax = fmaxf(__uint_as_float(rr[0]), __uint_as_float(rr[1])); }
;   float mn;
;   if (__builtin_expect(__all(pmax - m_reg <= THRS), 1)) { mn = m_reg; alpha = 1.f; }
;   else { mn = fmaxf(m_reg, pmax); alpha = __builtin_amdgcn_exp2f((m_reg - mn) * C); m_reg = mn; }
; template <int OFF> __device__ __forceinline__ s16x4 tr_read(int vb) {
;   s16x4 r; asm volatile("ds_read_b64_tr_b16 %0, %1 offset:%2" : "=&v"(r) : "v"(vb), "i"(OFF) : "memory"); return r;
; }
; template <int D0, int NCB> __device__ __forceinline__ void pv_one(f32x16& od, int vb, bf16x8 pa0, bf16x8 pa1, bf16x8 pa2, bf16x8 pa3) {
;   const s16x4 l0 = tr_read<v_rd_off<NCB>(D0, 0, 0)>(vb), h0 = tr_read<v_rd_off<NCB>(D0, 0, 1)>(vb), l1 = tr_read<v_rd_off<NCB>(D0, 1, 0)>(vb), h1 = tr_read<v_rd_off<NCB>(D0, 1, 1)>(vb);
;   const s16x4 l2 = tr_read<v_rd_off<NCB>(D0, 2, 0)>(vb), h2 = tr_read<v_rd_off<NCB>(D0, 2, 1)>(vb), l3 = tr_read<v_rd_off<NCB>(D0, 3, 0)>(vb), h3 = tr_read<v_rd_off<NCB>(D0, 3, 1)>(vb);
;   asm volatile("s_waitcnt lgkmcnt(0)" ::: "memory"); SBAR();
;     ...
;   od = __builtin_amdgcn_mfma_f32_32x32x16_bf16(pa0, PK(l0, h0), od, 0, 0, 0);
;   od = __builtin_amdgcn_mfma_f32_32x32x16_bf16(pa1, PK(l1, h1), od, 0, 0, 0);
;   od = __builtin_amdgcn_mfma_f32_32x32x16_bf16(pa2, PK(l2, h2), od, 0, 0, 0);
;   od = __builtin_amdgcn_mfma_f32_32x32x16_bf16(pa3, PK(l3, h3), od, 0, 0, 0);
;     ...
; }
; template <int NCB> __device__ __forceinline__ void pv_all(f32x16* o, int vb, bf16x8 pa0, bf16x8 pa1, bf16x8 pa2, bf16x8 pa3) {
;   pv_one<0, NCB>(o[0], vb, pa0, pa1, pa2, pa3); pv_one<1, NCB>(o[1], vb, pa0, pa1, pa2, pa3);
;   if constexpr (NCB == 4) { pv_one<2, NCB>(o[2], vb, pa0, pa1, pa2, pa3); pv_one<3, NCB>(o[3], vb, pa0, pa1, pa2, pa3); }
; }
	v_mfma_f32_32x32x16_bf16 v[176:191], v[240:243], v[252:255], v[176:191]
	v_add_f32_e32 v171, v90, v171
	v_cvt_pk_bf16_f32 v137, v82, v83
	v_add_f32_e32 v171, v91, v171
	v_mfma_f32_32x32x16_bf16 v[192:207], v[244:247], v[252:255], v[192:207]
	ds_read_b128 v[252:255], v248 offset:3072
	ds_read_b128 v[240:243], v163 offset:40960
	ds_read_b128 v[244:247], v163 offset:45056
	v_cvt_pk_bf16_f32 v138, v84, v85
	v_add_f32_e32 v171, v92, v171
	s_waitcnt lgkmcnt(10)
	v_mfma_f32_32x32x16_bf16 v[176:191], v[224:227], v[144:147], v[176:191]
	v_cvt_pk_bf16_f32 v139, v86, v87
	v_add_f32_e32 v171, v93, v171
	v_cvt_pk_bf16_f32 v140, v88, v89
	v_mfma_f32_32x32x16_bf16 v[192:207], v[228:231], v[144:147], v[192:207]
	v_add_f32_e32 v171, v94, v171
	v_cvt_pk_bf16_f32 v141, v90, v91
	s_waitcnt lgkmcnt(3)
	v_mfma_f32_32x32x16_bf16 v[176:191], v[232:235], v[148:151], v[176:191]
	v_add_f32_e32 v171, v95, v171
	v_cvt_pk_bf16_f32 v142, v92, v93
	v_add_f32_e32 v170, v171, v170
	v_mfma_f32_32x32x16_bf16 v[192:207], v[236:239], v[148:151], v[192:207]
	v_cvt_pk_bf16_f32 v143, v94, v95
	s_nop 0
	s_waitcnt lgkmcnt(0)
	v_mfma_f32_32x32x16_bf16 v[176:191], v[240:243], v[252:255], v[176:191]
	v_permlane32_swap_b32_e32 v136, v138
	v_permlane32_swap_b32_e32 v137, v139
	v_permlane32_swap_b32_e32 v140, v142
	v_mfma_f32_32x32x16_bf16 v[192:207], v[244:247], v[252:255], v[192:207]
	v_permlane32_swap_b32_e32 v141, v143
	ds_read_b64_tr_b16 v[80:81], v164 offset:512
	ds_read_b64_tr_b16 v[82:83], v164 offset:2560
	ds_read_b64_tr_b16 v[84:85], v164 offset:4608
	ds_read_b64_tr_b16 v[86:87], v164 offset:6656
	ds_read_b64_tr_b16 v[88:89], v164 offset:8704
	ds_read_b64_tr_b16 v[90:91], v164 offset:10752
	ds_read_b64_tr_b16 v[92:93], v164 offset:12800
	ds_read_b64_tr_b16 v[94:95], v164 offset:14848
	s_waitcnt lgkmcnt(14)
	v_mfma_f32_32x32x16_bf16 v[0:15], v[128:131], v[64:67], v[0:15]
	v_mfma_f32_32x32x16_bf16 v[0:15], v[132:135], v[68:71], v[0:15]
	ds_read_b64_tr_b16 v[64:65], v164 offset:1024
	ds_read_b64_tr_b16 v[66:67], v164 offset:3072
	ds_read_b64_tr_b16 v[68:69], v164 offset:5120
	ds_read_b64_tr_b16 v[70:71], v164 offset:7168
	v_mfma_f32_32x32x16_bf16 v[0:15], v[136:139], v[72:75], v[0:15]
	v_mfma_f32_32x32x16_bf16 v[0:15], v[140:143], v[76:79], v[0:15]
	ds_read_b64_tr_b16 v[72:73], v164 offset:9216
	ds_read_b64_tr_b16 v[74:75], v164 offset:11264
	ds_read_b64_tr_b16 v[76:77], v164 offset:13312
	ds_read_b64_tr_b16 v[78:79], v164 offset:15360
	s_waitcnt lgkmcnt(8)
	v_mfma_f32_32x32x16_bf16 v[48:63], v[128:131], v[80:83], v[48:63]
	v_max3_f32 v224, v176, v177, v178
	v_max3_f32 v225, v192, v193, v194
	v_max3_f32 v224, v224, v179, v180
	v_max3_f32 v225, v225, v195, v196
	v_max3_f32 v224, v224, v181, v182
	v_mfma_f32_32x32x16_bf16 v[48:63], v[132:135], v[84:87], v[48:63]
	v_max3_f32 v225, v225, v197, v198
	v_max3_f32 v224, v224, v183, v184
	v_max3_f32 v225, v225, v199, v200
	v_max3_f32 v224, v224, v185, v186
	v_max3_f32 v225, v225, v201, v202
	ds_read_b64_tr_b16 v[80:81], v164 offset:1536
	ds_read_b64_tr_b16 v[82:83], v164 offset:3584
	ds_read_b64_tr_b16 v[84:85], v164 offset:5632
	ds_read_b64_tr_b16 v[86:87], v164 offset:7680
	v_mfma_f32_32x32x16_bf16 v[48:63], v[136:139], v[88:91], v[48:63]
	v_max3_f32 v224, v224, v187, v188
	v_max3_f32 v225, v225, v203, v204
	v_max3_f32 v224, v224, v189, v190
	v_max3_f32 v225, v225, v205, v206
	v_max_f32_e32 v224, v191, v224
	v_mfma_f32_32x32x16_bf16 v[48:63], v[140:143], v[92:95], v[48:63]
	v_max_f32_e32 v225, v207, v225
	v_max_f32_e32 v226, v224, v225
	v_mov_b32_e32 v227, v226
	s_nop 1
	v_permlane32_swap_b32_e32 v226, v227
	v_max_f32_e32 v226, v226, v227
	ds_read_b64_tr_b16 v[88:89], v164 offset:9728
	ds_read_b64_tr_b16 v[90:91], v164 offset:11776
	ds_read_b64_tr_b16 v[92:93], v164 offset:13824
	ds_read_b64_tr_b16 v[94:95], v164 offset:15872
	s_waitcnt lgkmcnt(8)
	v_mfma_f32_32x32x16_bf16 v[32:47], v[128:131], v[64:67], v[32:47]
	v_cmp_lt_f32_e32 vcc, 0x4138aa3b, v226
	s_cbranch_vccnz .Lat_r1_lb

.LBB0_849:
	s_or_b64 exec, exec, s[6:7]
	v_mov_b32_e32 v0, 0
.LBB0_852:
	s_or_b64 exec, exec, s[2:3]

.LBB0_930:
	s_or_b64 exec, exec, s[6:7]
	v_mov_b32_e32 v0, 0
.LBB0_933:
	s_or_b64 exec, exec, s[2:3]

.LBB0_989:
	s_or_b64 exec, exec, s[6:7]
	v_mov_b32_e32 v0, 0
.LBB0_992:
	s_or_b64 exec, exec, s[2:3]

.LBB0_1024:
	s_or_b64 exec, exec, s[6:7]
	v_mov_b32_e32 v0, 0
.LBB0_1027:
	s_or_b64 exec, exec, s[2:3]

.LBB0_1105:
	s_or_b64 exec, exec, s[6:7]
	v_mov_b32_e32 v0, 0
.LBB0_1108:
	s_or_b64 exec, exec, s[2:3]

.LBB0_1164:
	s_or_b64 exec, exec, s[6:7]
	v_mov_b32_e32 v0, 0
.LBB0_1167:
	s_or_b64 exec, exec, s[2:3]

.LBB0_1321:
	s_or_b64 exec, exec, s[6:7]
	v_mov_b32_e32 v0, 0
.LBB0_1324:
	s_or_b64 exec, exec, s[2:3]

.LBB0_1399:
	s_or_b64 exec, exec, s[6:7]
	v_mov_b32_e32 v0, 0
.LBB0_1402:
	s_or_b64 exec, exec, s[2:3]

.LBB0_1460:
	s_or_b64 exec, exec, s[6:7]
	v_mov_b32_e32 v0, 0
.LBB0_1463:
	s_or_b64 exec, exec, s[2:3]

.LBB0_1486:
	s_andn2_b64 vcc, exec, s[0:1]
	s_add_i32 s74, s10, s78
	s_barrier
	s_barrier
	s_cbranch_vccnz .LBB0_1494
	v_mbcnt_lo_u32_b32 v0, -1, 0
	v_mbcnt_hi_u32_b32 v0, -1, v0
	s_nop 0
	v_cmp_eq_u32_e32 vcc, 0, v0
	s_and_saveexec_b64 s[0:1], vcc
	s_cbranch_execz .LBB0_1493
	s_mov_b64 s[4:5], exec
	v_mbcnt_lo_u32_b32 v0, s4, 0
	v_mbcnt_hi_u32_b32 v0, s5, v0
	v_cmp_eq_u32_e32 vcc, 0, v0
	s_and_saveexec_b64 s[6:7], vcc
	s_cbranch_execz .LBB0_1490
	s_bcnt1_i32_b64 s4, s[4:5]
	v_mov_b32_e32 v0, 0
	v_mov_b32_e32 v1, s4
	global_atomic_add v0, v1, s[22:23]
.LBB0_1490:
	s_or_b64 exec, exec, s[6:7]
	v_mov_b32_e32 v0, 0
.LBB0_1493:
	s_or_b64 exec, exec, s[0:1]

.LBB0_1533:
	s_or_b64 exec, exec, s[6:7]
	v_mov_b32_e32 v0, 0
.LBB0_1536:
	s_or_b64 exec, exec, s[2:3]

.LBB0_1590:
	s_andn2_b64 vcc, exec, s[2:3]
	s_barrier
	s_barrier
	s_cbranch_vccnz .LBB0_1598
	v_mbcnt_lo_u32_b32 v0, -1, 0
	v_mbcnt_hi_u32_b32 v0, -1, v0
	s_nop 0
	v_cmp_eq_u32_e32 vcc, 0, v0
	s_and_saveexec_b64 s[2:3], vcc
	s_cbranch_execz .LBB0_1597
	s_mov_b64 s[4:5], exec
	v_mbcnt_lo_u32_b32 v0, s4, 0
	v_mbcnt_hi_u32_b32 v0, s5, v0
	v_cmp_eq_u32_e32 vcc, 0, v0
	s_and_saveexec_b64 s[6:7], vcc
	s_cbranch_execz .LBB0_1594
	s_bcnt1_i32_b64 s4, s[4:5]
	v_mov_b32_e32 v0, 0
	v_mov_b32_e32 v1, s4
	global_atomic_add v0, v1, s[22:23]
.LBB0_1594:
	s_or_b64 exec, exec, s[6:7]
	v_mov_b32_e32 v0, 0
.LBB0_1597:
	s_or_b64 exec, exec, s[2:3]
